# fast attention loop heads aligned to 64 bytes (.p2align 6)
# baseline (speedup 1.0000x reference)
.Lfm_entry:
	s_mov_b32 s60, s58
	s_mov_b32 s58, s0
	v_add_u32_e32 v248, s58, v160
	ds_read_b128 v[164:167], v248 offset:13312
	ds_read_b128 v[168:171], v248 offset:17920
	ds_read_b128 v[172:175], v248 offset:13344
	ds_read_b128 v[176:179], v248 offset:17952
	ds_read_b128 v[180:183], v248 offset:13376
	ds_read_b128 v[220:223], v248 offset:17984
	ds_read_b128 v[224:227], v248 offset:13408
	ds_read_b128 v[232:235], v248 offset:18016
	.p2align	6

.Lfd_entry:
	s_mov_b32 s55, s51
	s_mov_b32 s51, s0
	v_add_u32_e32 v248, s51, v190
	ds_read_b128 v[196:199], v248 offset:9216
	ds_read_b128 v[200:203], v248 offset:13824
	ds_read_b128 v[204:207], v248 offset:18432
	ds_read_b128 v[208:211], v248 offset:23040
	ds_read_b128 v[212:215], v248 offset:9248
	ds_read_b128 v[216:219], v248 offset:13856
	ds_read_b128 v[220:223], v248 offset:18464
	ds_read_b128 v[224:227], v248 offset:23072
	.p2align	6
